# v_g2 + attention K/V LDS-DMA of waves 4-7 issued by waves 0-3 instead (8 pieces per tile each; waves 4-7 none)
# speedup vs baseline: 1.0008x; 1.0008x over previous
.LBB0_994:
	v_readfirstlane_b32 s89, v184
	s_nop 0
	s_cmpk_lt_u32 s89, 0x100
	s_cselect_b32 s89, s82, 0
	s_mov_b32 s6, m0
	s_mov_b32 m0, s63
	s_nop 0
	global_load_lds_dwordx4 v211, s[14:15]
	s_mov_b32 m0, s6
	s_add_i32 s6, s63, 0x2000
	s_mov_b32 s7, m0
	s_mov_b32 m0, s6
	s_nop 0
	global_load_lds_dwordx4 v211, s[18:19]
	s_mov_b32 m0, s7
	s_mov_b32 s6, m0
	s_mov_b32 m0, s68
	s_nop 0
	global_load_lds_dwordx4 v212, s[16:17]
	s_mov_b32 m0, s6
	v_mov_b32_e32 v128, 0x3f803f80
	s_add_i32 s6, s63, 0x6000
	s_mov_b32 s7, m0
	s_mov_b32 m0, s6
	s_nop 0
	global_load_lds_dwordx4 v212, s[20:21]
	s_mov_b32 m0, s7
	s_waitcnt vmcnt(8) lgkmcnt(0)
	s_barrier
	v_add_u32_e32 v4, v215, v170
	ds_read_b128 v[0:3], v4 offset:4096
	ds_read_b128 v[4:7], v4
	v_add_u32_e32 v12, v215, v172
	v_add_u32_e32 v20, v215, v173
	v_add_u32_e32 v28, v215, v174
	v_mov_b32_e32 v226, v161
	ds_read_b128 v[8:11], v12
	ds_read_b128 v[16:19], v12 offset:4096
	ds_read_b128 v[12:15], v20
	ds_read_b128 v[20:23], v20 offset:4096
	ds_read_b128 v[24:27], v28
	ds_read_b128 v[28:31], v28 offset:4096
	s_nop 0
	v_mov_b32_e32 v227, v161
	v_mov_b32_e32 v228, v161
	v_mov_b32_e32 v229, v161
	v_mov_b32_e32 v230, v161
	v_mov_b32_e32 v231, v161
	v_mov_b32_e32 v232, v161
	v_mov_b32_e32 v233, v161
	v_mov_b32_e32 v234, v161
	v_mov_b32_e32 v235, v161
	v_mov_b32_e32 v236, v161
	v_mov_b32_e32 v237, v161
	v_mov_b32_e32 v238, v161
	v_mov_b32_e32 v239, v161
	v_mov_b32_e32 v240, v161
	v_mov_b32_e32 v241, v161
	s_waitcnt lgkmcnt(6)
	s_nop 0
	v_mfma_f32_32x32x16_bf16 v[96:111], v[4:7], v[112:115], v[226:241]
	v_mfma_f32_32x32x16_bf16 v[80:95], v[0:3], v[112:115], v[226:241]
	s_waitcnt lgkmcnt(5)
	v_mfma_f32_32x32x16_bf16 v[96:111], v[8:11], v[116:119], v[96:111]
	s_waitcnt lgkmcnt(3)
	v_mfma_f32_32x32x16_bf16 v[96:111], v[12:15], v[120:123], v[96:111]
	ds_read_b64_tr_b16 v[0:1], v175
	ds_read_b64_tr_b16 v[2:3], v176
	ds_read_b64_tr_b16 v[4:5], v177
	ds_read_b64_tr_b16 v[6:7], v178
	ds_read_b64_tr_b16 v[8:9], v179
	ds_read_b64_tr_b16 v[10:11], v180
	ds_read_b64_tr_b16 v[12:13], v181
	ds_read_b64_tr_b16 v[14:15], v182
	s_waitcnt lgkmcnt(9)
	v_mfma_f32_32x32x16_bf16 v[96:111], v[24:27], v[124:127], v[96:111]
	v_mfma_f32_32x32x16_bf16 v[80:95], v[16:19], v[116:119], v[80:95]
	s_cmp_lg_u32 s89, 0
	s_cselect_b64 s[40:41], -1, 0
	s_cmp_eq_u32 s89, 0
	v_mfma_f32_32x32x16_bf16 v[80:95], v[20:23], v[120:123], v[80:95]
	s_waitcnt lgkmcnt(8)
	v_mfma_f32_32x32x16_bf16 v[80:95], v[28:31], v[124:127], v[80:95]
	s_cbranch_scc1 .LBB0_996
	s_add_i32 s6, s63, 0x8000
	s_mov_b32 s7, m0
	s_mov_b32 m0, s6
	s_nop 0
	global_load_lds_dwordx4 v211, s[22:23]
	s_mov_b32 m0, s7
	s_add_u32 s58, s22, 0x2c000
	s_addc_u32 s59, s23, 0
	s_add_i32 m0, s6, 0x1000
	s_nop 0
	global_load_lds_dwordx4 v211, s[58:59]
.LBB0_996:
	s_nop 3
	v_exp_f32_e32 v16, v96
	v_exp_f32_e32 v17, v97
	v_exp_f32_e32 v18, v98
	v_exp_f32_e32 v19, v99
	v_exp_f32_e32 v20, v100
	v_exp_f32_e32 v21, v101
	v_exp_f32_e32 v22, v102
	v_exp_f32_e32 v23, v103
	ds_read_b64_tr_b16 v[136:137], v183
	ds_read_b64_tr_b16 v[138:139], v186
	ds_read_b64_tr_b16 v[132:133], v187
	ds_read_b64_tr_b16 v[134:135], v188
	ds_read_b64_tr_b16 v[100:101], v189
	ds_read_b64_tr_b16 v[102:103], v190
	ds_read_b64_tr_b16 v[96:97], v191
	ds_read_b64_tr_b16 v[98:99], v192
	v_mov_b32_e32 v129, v128
	v_mov_b32_e32 v130, v128
	v_mov_b32_e32 v131, v128
	v_cvt_pk_bf16_f32 v64, v16, v17
	v_cvt_pk_bf16_f32 v65, v18, v19
	v_cvt_pk_bf16_f32 v66, v20, v21
	v_cvt_pk_bf16_f32 v67, v22, v23
	v_cndmask_b32_e64 v68, 0, 1, s[40:41]
	s_waitcnt lgkmcnt(14)
	v_mfma_f32_32x32x16_bf16 v[48:63], v[64:67], v[0:3], 0
	v_cmp_ne_u32_e64 s[6:7], 1, v68
	s_andn2_b64 vcc, exec, s[40:41]
	s_waitcnt lgkmcnt(12)
	v_mfma_f32_32x32x16_bf16 v[32:47], v[64:67], v[4:7], 0
	s_waitcnt lgkmcnt(10)
	v_mfma_f32_32x32x16_bf16 v[16:31], v[64:67], v[8:11], 0
	s_waitcnt lgkmcnt(8)
	v_mfma_f32_32x32x16_bf16 v[0:15], v[64:67], v[12:15], 0
	v_mfma_f32_32x32x16_bf16 v[64:79], v[64:67], v[128:131], 0
	s_cbranch_vccnz .LBB0_998
	s_add_i32 s40, s63, 0xa000
	s_mov_b32 s41, m0
	s_mov_b32 m0, s40
	s_nop 0
	global_load_lds_dwordx4 v211, s[24:25]
	s_mov_b32 m0, s41
	s_add_u32 s58, s24, 0x2c000
	s_addc_u32 s59, s25, 0
	s_add_i32 m0, s40, 0x1000
	s_nop 0
	global_load_lds_dwordx4 v211, s[58:59]
.LBB0_998:
	v_exp_f32_e32 v104, v104
	v_exp_f32_e32 v105, v105
	v_exp_f32_e32 v106, v106
	v_exp_f32_e32 v107, v107
	v_exp_f32_e32 v108, v108
	v_exp_f32_e32 v109, v109
	v_exp_f32_e32 v110, v110
	v_exp_f32_e32 v111, v111
	v_cvt_pk_bf16_f32 v148, v104, v105
	v_cvt_pk_bf16_f32 v149, v106, v107
	v_cvt_pk_bf16_f32 v150, v108, v109
	v_cvt_pk_bf16_f32 v151, v110, v111
	ds_read_b64_tr_b16 v[144:145], v193
	ds_read_b64_tr_b16 v[146:147], v194
	ds_read_b64_tr_b16 v[140:141], v195
	ds_read_b64_tr_b16 v[142:143], v196
	ds_read_b64_tr_b16 v[108:109], v197
	ds_read_b64_tr_b16 v[110:111], v198
	ds_read_b64_tr_b16 v[104:105], v199
	ds_read_b64_tr_b16 v[106:107], v200
	s_waitcnt lgkmcnt(14)
	v_mfma_f32_32x32x16_bf16 v[48:63], v[148:151], v[136:139], v[48:63]
	s_and_b64 vcc, exec, s[6:7]
	s_waitcnt lgkmcnt(12)
	v_mfma_f32_32x32x16_bf16 v[32:47], v[148:151], v[132:135], v[32:47]
	s_waitcnt lgkmcnt(10)
	v_mfma_f32_32x32x16_bf16 v[16:31], v[148:151], v[100:103], v[16:31]
	s_waitcnt lgkmcnt(8)
	v_mfma_f32_32x32x16_bf16 v[0:15], v[148:151], v[96:99], v[0:15]
	v_mfma_f32_32x32x16_bf16 v[64:79], v[148:151], v[128:131], v[64:79]
	s_cbranch_vccnz .LBB0_1000
	s_add_i32 s40, s63, 0xc000
	s_mov_b32 s41, m0
	s_mov_b32 m0, s40
	s_nop 0
	global_load_lds_dwordx4 v212, s[26:27]
	s_mov_b32 m0, s41
	s_add_u32 s58, s26, 0x40
	s_addc_u32 s59, s27, 0
	s_add_i32 m0, s40, 0x1000
	s_nop 0
	global_load_lds_dwordx4 v212, s[58:59]
.LBB0_1000:
	v_exp_f32_e32 v80, v80
	v_exp_f32_e32 v81, v81
	v_exp_f32_e32 v82, v82
	v_exp_f32_e32 v83, v83
	v_exp_f32_e32 v84, v84
	v_exp_f32_e32 v85, v85
	v_exp_f32_e32 v86, v86
	v_exp_f32_e32 v87, v87
	v_cvt_pk_bf16_f32 v132, v80, v81
	v_cvt_pk_bf16_f32 v133, v82, v83
	v_cvt_pk_bf16_f32 v134, v84, v85
	v_cvt_pk_bf16_f32 v135, v86, v87
	ds_read_b64_tr_b16 v[100:101], v201
	ds_read_b64_tr_b16 v[102:103], v202
	ds_read_b64_tr_b16 v[96:97], v203
	ds_read_b64_tr_b16 v[98:99], v204
	ds_read_b64_tr_b16 v[84:85], v205
	ds_read_b64_tr_b16 v[86:87], v206
	ds_read_b64_tr_b16 v[80:81], v207
	ds_read_b64_tr_b16 v[82:83], v208
	s_waitcnt lgkmcnt(14)
	v_mfma_f32_32x32x16_bf16 v[48:63], v[132:135], v[144:147], v[48:63]
	s_and_b64 vcc, exec, s[6:7]
	s_waitcnt lgkmcnt(12)
	v_mfma_f32_32x32x16_bf16 v[32:47], v[132:135], v[140:143], v[32:47]
	s_waitcnt lgkmcnt(10)
	v_mfma_f32_32x32x16_bf16 v[16:31], v[132:135], v[108:111], v[16:31]
	s_waitcnt lgkmcnt(8)
	v_mfma_f32_32x32x16_bf16 v[0:15], v[132:135], v[104:107], v[0:15]
	v_mfma_f32_32x32x16_bf16 v[64:79], v[132:135], v[128:131], v[64:79]
	s_cbranch_vccnz .LBB0_1002
	s_add_i32 s6, s63, 0xe000
	s_mov_b32 s7, m0
	s_mov_b32 m0, s6
	s_nop 0
	global_load_lds_dwordx4 v212, s[28:29]
	s_mov_b32 m0, s7
	s_add_u32 s58, s28, 0x40
	s_addc_u32 s59, s29, 0
	s_add_i32 m0, s6, 0x1000
	s_nop 0
	global_load_lds_dwordx4 v212, s[58:59]
.LBB0_1002:
	v_exp_f32_e32 v88, v88
	v_exp_f32_e32 v89, v89
	v_exp_f32_e32 v90, v90
	v_exp_f32_e32 v91, v91
	v_exp_f32_e32 v92, v92
	v_exp_f32_e32 v93, v93
	v_exp_f32_e32 v94, v94
	v_exp_f32_e32 v95, v95
	s_lshl_b32 s83, s82, 1
	s_lshl_b32 s32, s89, 1
	v_cvt_pk_bf16_f32 v88, v88, v89
	v_cvt_pk_bf16_f32 v89, v90, v91
	v_cvt_pk_bf16_f32 v90, v92, v93
	v_cvt_pk_bf16_f32 v91, v94, v95
	s_add_i32 s6, s79, s83
	s_waitcnt lgkmcnt(6)
	v_mfma_f32_32x32x16_bf16 v[48:63], v[88:91], v[100:103], v[48:63]
	s_cmp_eq_u32 s6, 1
	s_waitcnt lgkmcnt(4)
	v_mfma_f32_32x32x16_bf16 v[32:47], v[88:91], v[96:99], v[32:47]
	s_waitcnt lgkmcnt(2)
	v_mfma_f32_32x32x16_bf16 v[16:31], v[88:91], v[84:87], v[16:31]
	s_waitcnt lgkmcnt(0)
	v_mfma_f32_32x32x16_bf16 v[0:15], v[88:91], v[80:83], v[0:15]
	v_mfma_f32_32x32x16_bf16 v[64:79], v[88:91], v[128:131], v[64:79]
	s_cbranch_scc1 .LBB0_1017
	s_add_i32 s84, s69, s83
	s_mov_b32 s86, 0x10000
	s_mov_b32 s85, 0
	s_mov_b64 s[40:41], s[38:39]
	s_mov_b64 s[42:43], s[36:37]
	s_mov_b64 s[48:49], s[34:35]
	s_mov_b32 s87, 0
	s_branch .LBB0_1005

.LBB0_1005:
	s_add_i32 s85, s85, 1
	s_cmp_gt_u32 s85, s32
	s_mov_b64 s[6:7], -1
	s_cbranch_scc1 .LBB0_1007
	s_waitcnt vmcnt(8) lgkmcnt(0)
	s_barrier
	s_mov_b64 s[6:7], 0

.LBB0_1009:
	v_add_u32_e32 v80, s87, v213
	v_add_u32_e32 v81, v80, v170
	ds_read_b128 v[132:135], v81
	ds_read_b128 v[136:139], v81 offset:4096
	v_add_u32_e32 v81, v80, v172
	ds_read_b128 v[140:143], v81
	ds_read_b128 v[148:151], v81 offset:4096
	v_add_u32_e32 v81, v80, v173
	v_add_u32_e32 v80, v80, v174
	ds_read_b128 v[144:147], v81
	ds_read_b128 v[152:155], v81 offset:4096
	ds_read_b128 v[216:219], v80
	ds_read_b128 v[220:223], v80 offset:4096
	v_add_u32_e32 v156, s87, v171
	s_waitcnt lgkmcnt(7)
	v_mfma_f32_32x32x16_bf16 v[96:111], v[132:135], v[112:115], v[226:241]
	s_waitcnt lgkmcnt(6)
	v_mfma_f32_32x32x16_bf16 v[80:95], v[136:139], v[112:115], v[226:241]
	s_waitcnt lgkmcnt(5)
	v_mfma_f32_32x32x16_bf16 v[96:111], v[140:143], v[116:119], v[96:111]
	s_waitcnt lgkmcnt(3)
	v_mfma_f32_32x32x16_bf16 v[96:111], v[144:147], v[120:123], v[96:111]
	ds_read_b64_tr_b16 v[144:145], v156 offset:16384
	ds_read_b64_tr_b16 v[146:147], v156 offset:16896
	ds_read_b64_tr_b16 v[140:141], v156 offset:20480
	ds_read_b64_tr_b16 v[142:143], v156 offset:20992
	ds_read_b64_tr_b16 v[136:137], v156 offset:24576
	ds_read_b64_tr_b16 v[138:139], v156 offset:25088
	ds_read_b64_tr_b16 v[132:133], v156 offset:28672
	ds_read_b64_tr_b16 v[134:135], v156 offset:29184
	s_waitcnt lgkmcnt(9)
	v_mfma_f32_32x32x16_bf16 v[96:111], v[216:219], v[124:127], v[96:111]
	v_mfma_f32_32x32x16_bf16 v[80:95], v[148:151], v[116:119], v[80:95]
	s_cmp_lt_u32 s85, s32
	s_cselect_b64 s[50:51], -1, 0
	s_cmp_ge_u32 s85, s32
	v_mfma_f32_32x32x16_bf16 v[80:95], v[152:155], v[120:123], v[80:95]
	s_waitcnt lgkmcnt(8)
	v_mfma_f32_32x32x16_bf16 v[80:95], v[220:223], v[124:127], v[80:95]
.LBB0_1011:
	s_nop 3
	v_exp_f32_e32 v96, v96
	v_exp_f32_e32 v97, v97
	v_exp_f32_e32 v98, v98
	v_exp_f32_e32 v99, v99
	v_exp_f32_e32 v100, v100
	v_exp_f32_e32 v101, v101
	v_exp_f32_e32 v102, v102
	v_exp_f32_e32 v103, v103
	v_cvt_pk_bf16_f32 v216, v96, v97
	v_cvt_pk_bf16_f32 v217, v98, v99
	v_cvt_pk_bf16_f32 v218, v100, v101
	v_cvt_pk_bf16_f32 v219, v102, v103
	s_cbranch_scc1 .Latt_dma0
	s_add_i32 s6, s86, s63
	s_mov_b32 s7, m0
	s_mov_b32 m0, s6
	s_nop 0
	global_load_lds_dwordx4 v211, s[48:49]
	s_mov_b32 m0, s7
	s_add_u32 s58, s48, 0x2c000
	s_addc_u32 s59, s49, 0
	s_add_i32 m0, s6, 0x1000
	s_nop 0
	global_load_lds_dwordx4 v211, s[58:59]

.LBB0_1013:
	v_exp_f32_e32 v104, v104
	v_exp_f32_e32 v105, v105
	v_exp_f32_e32 v106, v106
	v_exp_f32_e32 v107, v107
	v_exp_f32_e32 v108, v108
	v_exp_f32_e32 v109, v109
	v_exp_f32_e32 v110, v110
	v_exp_f32_e32 v111, v111
	v_cvt_pk_bf16_f32 v140, v104, v105
	v_cvt_pk_bf16_f32 v141, v106, v107
	v_cvt_pk_bf16_f32 v142, v108, v109
	v_cvt_pk_bf16_f32 v143, v110, v111
	s_cbranch_vccnz .Latt_dma1
	s_add_u32 s50, s42, 0x80
	s_addc_u32 s51, s43, 0
	s_add_i32 s58, s86, s63
	s_addk_i32 s58, 0x2000
	s_mov_b32 s59, m0
	s_mov_b32 m0, s58
	s_nop 0
	global_load_lds_dwordx4 v211, s[50:51]
	s_mov_b32 m0, s59
	s_add_i32 m0, s58, 0x1000
	s_add_u32 s58, s50, 0x2c000
	s_addc_u32 s59, s51, 0
	global_load_lds_dwordx4 v211, s[58:59]

.LBB0_1015:
	v_exp_f32_e32 v80, v80
	v_exp_f32_e32 v81, v81
	v_exp_f32_e32 v82, v82
	v_exp_f32_e32 v83, v83
	v_exp_f32_e32 v84, v84
	v_exp_f32_e32 v85, v85
	v_exp_f32_e32 v86, v86
	v_exp_f32_e32 v87, v87
	v_cvt_pk_bf16_f32 v140, v80, v81
	v_cvt_pk_bf16_f32 v141, v82, v83
	v_cvt_pk_bf16_f32 v142, v84, v85
	v_cvt_pk_bf16_f32 v143, v86, v87
	s_cbranch_vccnz .Latt_dma2
	s_add_i32 s50, s86, s68
	s_mov_b32 s51, m0
	s_mov_b32 m0, s50
	s_nop 0
	global_load_lds_dwordx4 v212, s[40:41]
	s_mov_b32 m0, s51
	s_add_u32 s58, s40, 0x40
	s_addc_u32 s59, s41, 0
	s_add_i32 m0, s50, 0x1000
	s_nop 0
	global_load_lds_dwordx4 v212, s[58:59]
.Latt_dma2:
	ds_read_b64_tr_b16 v[100:101], v156 offset:19456
	ds_read_b64_tr_b16 v[102:103], v156 offset:19968
	ds_read_b64_tr_b16 v[96:97], v156 offset:23552
	ds_read_b64_tr_b16 v[98:99], v156 offset:24064
	ds_read_b64_tr_b16 v[84:85], v156 offset:27648
	ds_read_b64_tr_b16 v[86:87], v156 offset:28160
	ds_read_b64_tr_b16 v[80:81], v156 offset:31744
	ds_read_b64_tr_b16 v[82:83], v156 offset:32256
	s_waitcnt lgkmcnt(14)
	v_mfma_f32_32x32x16_bf16 v[48:63], v[140:143], v[136:139], v[48:63]
	s_and_b64 vcc, exec, s[6:7]
	s_waitcnt lgkmcnt(12)
	v_mfma_f32_32x32x16_bf16 v[32:47], v[140:143], v[132:135], v[32:47]
	s_waitcnt lgkmcnt(10)
	v_mfma_f32_32x32x16_bf16 v[16:31], v[140:143], v[108:111], v[16:31]
	s_waitcnt lgkmcnt(8)
	v_mfma_f32_32x32x16_bf16 v[0:15], v[140:143], v[104:107], v[0:15]
	v_mfma_f32_32x32x16_bf16 v[64:79], v[140:143], v[128:131], v[64:79]
	s_cbranch_vccnz .LBB0_1004
	s_add_u32 s6, s42, 0x480
	s_addc_u32 s7, s43, 0
	s_add_i32 s50, s86, s68
	s_addk_i32 s50, 0x2000
	s_mov_b32 s51, m0
	s_mov_b32 m0, s50
	s_nop 0
	global_load_lds_dwordx4 v212, s[6:7]
	s_mov_b32 m0, s51
	s_add_u32 s58, s6, 0x40
	s_addc_u32 s59, s7, 0
	s_add_i32 m0, s50, 0x1000
	s_nop 0
	global_load_lds_dwordx4 v212, s[58:59]
	s_branch .LBB0_1004
